# lane-transposed epilogues (quarter-wave touches 4 rows x 1 line) for out-proj, MLP-up, last down GEMM; cvt_pk packing; 2-deep residual prefetch
# speedup vs baseline: 1.0162x; 1.0067x over previous
.LBB0_1065:
	v_mbcnt_lo_u32_b32 v200, -1, 0
	v_mbcnt_hi_u32_b32 v200, -1, v200
	v_and_b32_e32 v201, 15, v200
	v_lshrrev_b32_e32 v182, 2, v200
	v_sub_u32_e32 v201, v182, v201
	v_add_u32_e32 v201, v196, v201
	v_lshrrev_b32_e32 v169, 4, v200
	v_and_b32_e32 v194, 3, v200
	v_sub_u32_e32 v169, v194, v169
	v_lshl_add_u32 v169, v169, 3, v198
	v_lshl_or_b32 v168, s27, 8, v169
	v_lshlrev_b32_e32 v183, 2, v168
	v_lshl_add_u32 v195, v194, 4, v182
	v_lshlrev_b32_e32 v195, 2, v195
	v_xor_b32_e32 v188, 1, v200
	v_lshlrev_b32_e32 v188, 2, v188
	v_xor_b32_e32 v200, 2, v200
	v_lshlrev_b32_e32 v200, 2, v200
	ds_bpermute_b32 v208, v195, v72
	ds_bpermute_b32 v209, v195, v73
	ds_bpermute_b32 v210, v195, v74
	ds_bpermute_b32 v211, v195, v75
	ds_bpermute_b32 v212, v195, v80
	ds_bpermute_b32 v213, v195, v81
	ds_bpermute_b32 v214, v195, v82
	ds_bpermute_b32 v215, v195, v83
	s_waitcnt lgkmcnt(7)
	ds_bpermute_b32 v216, v195, v64
	ds_bpermute_b32 v217, v195, v65
	ds_bpermute_b32 v218, v195, v66
	ds_bpermute_b32 v219, v195, v67
	ds_bpermute_b32 v220, v195, v68
	ds_bpermute_b32 v221, v195, v69
	ds_bpermute_b32 v222, v195, v70
	ds_bpermute_b32 v223, v195, v71
	s_waitcnt lgkmcnt(0)
	v_mov_b64_e32 v[72:73], v[208:209]
	v_mov_b64_e32 v[74:75], v[210:211]
	v_mov_b64_e32 v[80:81], v[212:213]
	v_mov_b64_e32 v[82:83], v[214:215]
	v_mov_b64_e32 v[64:65], v[216:217]
	v_mov_b64_e32 v[66:67], v[218:219]
	v_mov_b64_e32 v[68:69], v[220:221]
	v_mov_b64_e32 v[70:71], v[222:223]
	ds_bpermute_b32 v154, v195, v174
	ds_bpermute_b32 v155, v195, v175
	ds_bpermute_b32 v156, v195, v176
	ds_bpermute_b32 v157, v195, v177
	ds_bpermute_b32 v158, v195, v184
	ds_bpermute_b32 v159, v195, v185
	ds_bpermute_b32 v160, v195, v186
	ds_bpermute_b32 v161, v195, v187
	s_waitcnt lgkmcnt(7)
	ds_bpermute_b32 v162, v195, v170
	ds_bpermute_b32 v163, v195, v171
	ds_bpermute_b32 v164, v195, v172
	ds_bpermute_b32 v165, v195, v173
	ds_bpermute_b32 v224, v195, v178
	ds_bpermute_b32 v225, v195, v179
	ds_bpermute_b32 v226, v195, v180
	ds_bpermute_b32 v227, v195, v181
	s_waitcnt lgkmcnt(0)
	v_mov_b64_e32 v[174:175], v[154:155]
	v_mov_b64_e32 v[176:177], v[156:157]
	v_mov_b64_e32 v[184:185], v[158:159]
	v_mov_b64_e32 v[186:187], v[160:161]
	v_mov_b64_e32 v[170:171], v[162:163]
	v_mov_b64_e32 v[172:173], v[164:165]
	v_mov_b64_e32 v[178:179], v[224:225]
	v_mov_b64_e32 v[180:181], v[226:227]
	ds_bpermute_b32 v154, v195, v124
	ds_bpermute_b32 v155, v195, v125
	ds_bpermute_b32 v156, v195, v126
	ds_bpermute_b32 v157, v195, v127
	ds_bpermute_b32 v158, v195, v120
	ds_bpermute_b32 v159, v195, v121
	ds_bpermute_b32 v160, v195, v122
	ds_bpermute_b32 v161, v195, v123
	s_waitcnt lgkmcnt(7)
	ds_bpermute_b32 v162, v195, v116
	ds_bpermute_b32 v163, v195, v117
	ds_bpermute_b32 v164, v195, v118
	ds_bpermute_b32 v165, v195, v119
	ds_bpermute_b32 v224, v195, v112
	ds_bpermute_b32 v225, v195, v113
	ds_bpermute_b32 v226, v195, v114
	ds_bpermute_b32 v227, v195, v115
	s_lshl_b32 s15, s26, 8
	s_add_i32 s17, s15, 0xffff8000
	s_and_b64 s[22:23], s[22:23], exec
	s_cselect_b32 s17, s15, s17
	s_cselect_b32 s23, s35, s56
	s_cselect_b32 s22, s53, s94
	v_readlane_b32 s100, v253, 59
	s_nop 0
	s_cselect_b32 s25, s75, s100
	v_readlane_b32 s100, v253, 58
	s_nop 0
	s_cselect_b32 s24, s74, s100
	v_readlane_b32 s26, v254, 49
	v_readlane_b32 s27, v254, 50
	v_add_u32_e32 v189, s17, v201
	v_lshl_add_u32 v189, v189, 10, v168
	v_lshlrev_b32_e32 v189, 2, v189
	v_add_u32_e32 v191, s15, v201
	v_lshl_add_u32 v190, v191, 10, v168
	v_lshlrev_b32_e32 v190, 1, v190
	v_lshlrev_b32_e32 v191, 2, v191
	v_cmp_eq_u32_e32 vcc, 0, v194
	s_waitcnt vmcnt(0)
	s_waitcnt lgkmcnt(0)
	ds_bpermute_b32 v208, v195, v140
	ds_bpermute_b32 v209, v195, v141
	ds_bpermute_b32 v210, v195, v142
	ds_bpermute_b32 v211, v195, v143
	ds_bpermute_b32 v212, v195, v136
	ds_bpermute_b32 v213, v195, v137
	ds_bpermute_b32 v214, v195, v138
	ds_bpermute_b32 v215, v195, v139
	s_waitcnt lgkmcnt(7)
	ds_bpermute_b32 v216, v195, v132
	ds_bpermute_b32 v217, v195, v133
	ds_bpermute_b32 v218, v195, v134
	ds_bpermute_b32 v219, v195, v135
	ds_bpermute_b32 v220, v195, v128
	ds_bpermute_b32 v221, v195, v129
	ds_bpermute_b32 v222, v195, v130
	ds_bpermute_b32 v223, v195, v131
	s_waitcnt lgkmcnt(0)
	global_load_dwordx4 v[140:143], v189, s[22:23]
	global_load_dwordx4 v[136:139], v189, s[22:23] offset:16
	global_load_dwordx4 v[132:135], v189, s[22:23] offset:512
	global_load_dwordx4 v[128:131], v189, s[22:23] offset:528
	s_add_u32 s22, s22, 0x10000
	s_addc_u32 s23, s23, 0
	global_load_dwordx4 v[124:127], v189, s[22:23]
	global_load_dwordx4 v[120:123], v189, s[22:23] offset:16
	global_load_dwordx4 v[116:119], v189, s[22:23] offset:512
	global_load_dwordx4 v[112:115], v189, s[22:23] offset:528
	s_add_u32 s22, s22, 0x10000
	s_addc_u32 s23, s23, 0
	s_waitcnt vmcnt(4)
	v_pk_fma_f32 v[140:141], v[208:209], v[72:73], v[140:141]
	v_pk_fma_f32 v[142:143], v[210:211], v[74:75], v[142:143]
	v_pk_fma_f32 v[136:137], v[212:213], v[80:81], v[136:137]
	v_pk_fma_f32 v[138:139], v[214:215], v[82:83], v[138:139]
	v_pk_fma_f32 v[132:133], v[216:217], v[64:65], v[132:133]
	v_pk_fma_f32 v[134:135], v[218:219], v[66:67], v[134:135]
	v_pk_fma_f32 v[128:129], v[220:221], v[68:69], v[128:129]
	v_pk_fma_f32 v[130:131], v[222:223], v[70:71], v[130:131]
	ds_bpermute_b32 v208, v195, v108
	ds_bpermute_b32 v209, v195, v109
	ds_bpermute_b32 v210, v195, v110
	ds_bpermute_b32 v211, v195, v111
	ds_bpermute_b32 v212, v195, v104
	ds_bpermute_b32 v213, v195, v105
	ds_bpermute_b32 v214, v195, v106
	ds_bpermute_b32 v215, v195, v107
	global_store_dwordx4 v189, v[140:143], s[24:25]
	global_store_dwordx4 v189, v[136:139], s[24:25] offset:16
	global_store_dwordx4 v189, v[132:135], s[24:25] offset:512
	global_store_dwordx4 v189, v[128:131], s[24:25] offset:528
	s_add_u32 s24, s24, 0x10000
	s_addc_u32 s25, s25, 0
	s_waitcnt lgkmcnt(6)
	ds_bpermute_b32 v216, v195, v100
	ds_bpermute_b32 v217, v195, v101
	ds_bpermute_b32 v218, v195, v102
	ds_bpermute_b32 v219, v195, v103
	ds_bpermute_b32 v220, v195, v96
	ds_bpermute_b32 v221, v195, v97
	ds_bpermute_b32 v222, v195, v98
	ds_bpermute_b32 v223, v195, v99
	v_pk_mul_f32 v[168:169], v[140:141], v[140:141]
	v_pk_fma_f32 v[168:169], v[142:143], v[142:143], v[168:169]
	v_pk_fma_f32 v[168:169], v[136:137], v[136:137], v[168:169]
	v_pk_fma_f32 v[168:169], v[138:139], v[138:139], v[168:169]
	v_pk_fma_f32 v[168:169], v[132:133], v[132:133], v[168:169]
	v_pk_fma_f32 v[168:169], v[134:135], v[134:135], v[168:169]
	v_pk_fma_f32 v[168:169], v[128:129], v[128:129], v[168:169]
	v_pk_fma_f32 v[168:169], v[130:131], v[130:131], v[168:169]
	v_add_f32_e32 v193, v168, v169
	ds_bpermute_b32 v192, v188, v193
	v_pk_mul_f32 v[140:141], v[174:175], v[140:141]
	v_pk_mul_f32 v[142:143], v[176:177], v[142:143]
	v_pk_mul_f32 v[136:137], v[184:185], v[136:137]
	v_pk_mul_f32 v[138:139], v[186:187], v[138:139]
	v_pk_mul_f32 v[132:133], v[170:171], v[132:133]
	v_pk_mul_f32 v[134:135], v[172:173], v[134:135]
	v_pk_mul_f32 v[128:129], v[178:179], v[128:129]
	v_pk_mul_f32 v[130:131], v[180:181], v[130:131]
	s_waitcnt lgkmcnt(0)
	v_add_f32_e32 v193, v193, v192
	ds_bpermute_b32 v192, v200, v193
	v_cvt_pk_bf16_f32 v140, v140, v141
	v_cvt_pk_bf16_f32 v141, v142, v143
	v_cvt_pk_bf16_f32 v142, v136, v137
	v_cvt_pk_bf16_f32 v143, v138, v139
	v_cvt_pk_bf16_f32 v132, v132, v133
	v_cvt_pk_bf16_f32 v133, v134, v135
	v_cvt_pk_bf16_f32 v134, v128, v129
	v_cvt_pk_bf16_f32 v135, v130, v131
	s_waitcnt lgkmcnt(0)
	v_add_f32_e32 v193, v193, v192
	global_store_dwordx4 v190, v[140:143], s[26:27]
	global_store_dwordx4 v190, v[132:135], s[26:27] offset:256
	s_add_u32 s26, s26, 0x8000
	s_addc_u32 s27, s27, 0
	s_and_saveexec_b64 s[100:101], vcc
	s_cbranch_execz .Lepit_op_na0
	global_atomic_add_f32 v191, v193, s[54:55]
.Lepit_op_na0:
	s_or_b64 exec, exec, s[100:101]
	s_waitcnt lgkmcnt(0)
	global_load_dwordx4 v[108:111], v189, s[22:23]
	global_load_dwordx4 v[104:107], v189, s[22:23] offset:16
	global_load_dwordx4 v[100:103], v189, s[22:23] offset:512
	global_load_dwordx4 v[96:99], v189, s[22:23] offset:528
	s_add_u32 s22, s22, 0x10000
	s_addc_u32 s23, s23, 0
	s_waitcnt vmcnt(10)
	v_pk_fma_f32 v[124:125], v[154:155], v[72:73], v[124:125]
	v_pk_fma_f32 v[126:127], v[156:157], v[74:75], v[126:127]
	v_pk_fma_f32 v[120:121], v[158:159], v[80:81], v[120:121]
	v_pk_fma_f32 v[122:123], v[160:161], v[82:83], v[122:123]
	v_pk_fma_f32 v[116:117], v[162:163], v[64:65], v[116:117]
	v_pk_fma_f32 v[118:119], v[164:165], v[66:67], v[118:119]
	v_pk_fma_f32 v[112:113], v[224:225], v[68:69], v[112:113]
	v_pk_fma_f32 v[114:115], v[226:227], v[70:71], v[114:115]
	ds_bpermute_b32 v154, v195, v92
	ds_bpermute_b32 v155, v195, v93
	ds_bpermute_b32 v156, v195, v94
	ds_bpermute_b32 v157, v195, v95
	ds_bpermute_b32 v158, v195, v88
	ds_bpermute_b32 v159, v195, v89
	ds_bpermute_b32 v160, v195, v90
	ds_bpermute_b32 v161, v195, v91
	global_store_dwordx4 v189, v[124:127], s[24:25]
	global_store_dwordx4 v189, v[120:123], s[24:25] offset:16
	global_store_dwordx4 v189, v[116:119], s[24:25] offset:512
	global_store_dwordx4 v189, v[112:115], s[24:25] offset:528
	s_add_u32 s24, s24, 0x10000
	s_addc_u32 s25, s25, 0
	s_waitcnt lgkmcnt(6)
	ds_bpermute_b32 v162, v195, v84
	ds_bpermute_b32 v163, v195, v85
	ds_bpermute_b32 v164, v195, v86
	ds_bpermute_b32 v165, v195, v87
	ds_bpermute_b32 v224, v195, v76
	ds_bpermute_b32 v225, v195, v77
	ds_bpermute_b32 v226, v195, v78
	ds_bpermute_b32 v227, v195, v79
	v_pk_mul_f32 v[168:169], v[124:125], v[124:125]
	v_pk_fma_f32 v[168:169], v[126:127], v[126:127], v[168:169]
	v_pk_fma_f32 v[168:169], v[120:121], v[120:121], v[168:169]
	v_pk_fma_f32 v[168:169], v[122:123], v[122:123], v[168:169]
	v_pk_fma_f32 v[168:169], v[116:117], v[116:117], v[168:169]
	v_pk_fma_f32 v[168:169], v[118:119], v[118:119], v[168:169]
	v_pk_fma_f32 v[168:169], v[112:113], v[112:113], v[168:169]
	v_pk_fma_f32 v[168:169], v[114:115], v[114:115], v[168:169]
	v_add_f32_e32 v193, v168, v169
	ds_bpermute_b32 v192, v188, v193
	v_pk_mul_f32 v[124:125], v[174:175], v[124:125]
	v_pk_mul_f32 v[126:127], v[176:177], v[126:127]
	v_pk_mul_f32 v[120:121], v[184:185], v[120:121]
	v_pk_mul_f32 v[122:123], v[186:187], v[122:123]
	v_pk_mul_f32 v[116:117], v[170:171], v[116:117]
	v_pk_mul_f32 v[118:119], v[172:173], v[118:119]
	v_pk_mul_f32 v[112:113], v[178:179], v[112:113]
	v_pk_mul_f32 v[114:115], v[180:181], v[114:115]
	s_waitcnt lgkmcnt(0)
	v_add_f32_e32 v193, v193, v192
	ds_bpermute_b32 v192, v200, v193
	v_cvt_pk_bf16_f32 v124, v124, v125
	v_cvt_pk_bf16_f32 v125, v126, v127
	v_cvt_pk_bf16_f32 v126, v120, v121
	v_cvt_pk_bf16_f32 v127, v122, v123
	v_cvt_pk_bf16_f32 v116, v116, v117
	v_cvt_pk_bf16_f32 v117, v118, v119
	v_cvt_pk_bf16_f32 v118, v112, v113
	v_cvt_pk_bf16_f32 v119, v114, v115
	s_waitcnt lgkmcnt(0)
	v_add_f32_e32 v193, v193, v192
	global_store_dwordx4 v190, v[124:127], s[26:27]
	global_store_dwordx4 v190, v[116:119], s[26:27] offset:256
	s_add_u32 s26, s26, 0x8000
	s_addc_u32 s27, s27, 0
	s_and_saveexec_b64 s[100:101], vcc
	s_cbranch_execz .Lepit_op_na1
	global_atomic_add_f32 v191, v193, s[54:55] offset:64
.Lepit_op_na1:
	s_or_b64 exec, exec, s[100:101]
	s_waitcnt lgkmcnt(0)
	global_load_dwordx4 v[92:95], v189, s[22:23]
	global_load_dwordx4 v[88:91], v189, s[22:23] offset:16
	global_load_dwordx4 v[84:87], v189, s[22:23] offset:512
	global_load_dwordx4 v[76:79], v189, s[22:23] offset:528
	s_add_u32 s22, s22, 0x50000
	s_addc_u32 s23, s23, 0
	s_waitcnt vmcnt(10)
	v_pk_fma_f32 v[108:109], v[208:209], v[72:73], v[108:109]
	v_pk_fma_f32 v[110:111], v[210:211], v[74:75], v[110:111]
	v_pk_fma_f32 v[104:105], v[212:213], v[80:81], v[104:105]
	v_pk_fma_f32 v[106:107], v[214:215], v[82:83], v[106:107]
	v_pk_fma_f32 v[100:101], v[216:217], v[64:65], v[100:101]
	v_pk_fma_f32 v[102:103], v[218:219], v[66:67], v[102:103]
	v_pk_fma_f32 v[96:97], v[220:221], v[68:69], v[96:97]
	v_pk_fma_f32 v[98:99], v[222:223], v[70:71], v[98:99]
	ds_bpermute_b32 v208, v195, v60
	ds_bpermute_b32 v209, v195, v61
	ds_bpermute_b32 v210, v195, v62
	ds_bpermute_b32 v211, v195, v63
	ds_bpermute_b32 v212, v195, v56
	ds_bpermute_b32 v213, v195, v57
	ds_bpermute_b32 v214, v195, v58
	ds_bpermute_b32 v215, v195, v59
	global_store_dwordx4 v189, v[108:111], s[24:25]
	global_store_dwordx4 v189, v[104:107], s[24:25] offset:16
	global_store_dwordx4 v189, v[100:103], s[24:25] offset:512
	global_store_dwordx4 v189, v[96:99], s[24:25] offset:528
	s_add_u32 s24, s24, 0x10000
	s_addc_u32 s25, s25, 0
	s_waitcnt lgkmcnt(6)
	ds_bpermute_b32 v216, v195, v52
	ds_bpermute_b32 v217, v195, v53
	ds_bpermute_b32 v218, v195, v54
	ds_bpermute_b32 v219, v195, v55
	ds_bpermute_b32 v220, v195, v48
	ds_bpermute_b32 v221, v195, v49
	ds_bpermute_b32 v222, v195, v50
	ds_bpermute_b32 v223, v195, v51
	v_pk_mul_f32 v[168:169], v[108:109], v[108:109]
	v_pk_fma_f32 v[168:169], v[110:111], v[110:111], v[168:169]
	v_pk_fma_f32 v[168:169], v[104:105], v[104:105], v[168:169]
	v_pk_fma_f32 v[168:169], v[106:107], v[106:107], v[168:169]
	v_pk_fma_f32 v[168:169], v[100:101], v[100:101], v[168:169]
	v_pk_fma_f32 v[168:169], v[102:103], v[102:103], v[168:169]
	v_pk_fma_f32 v[168:169], v[96:97], v[96:97], v[168:169]
	v_pk_fma_f32 v[168:169], v[98:99], v[98:99], v[168:169]
	v_add_f32_e32 v193, v168, v169
	ds_bpermute_b32 v192, v188, v193
	v_pk_mul_f32 v[108:109], v[174:175], v[108:109]
	v_pk_mul_f32 v[110:111], v[176:177], v[110:111]
	v_pk_mul_f32 v[104:105], v[184:185], v[104:105]
	v_pk_mul_f32 v[106:107], v[186:187], v[106:107]
	v_pk_mul_f32 v[100:101], v[170:171], v[100:101]
	v_pk_mul_f32 v[102:103], v[172:173], v[102:103]
	v_pk_mul_f32 v[96:97], v[178:179], v[96:97]
	v_pk_mul_f32 v[98:99], v[180:181], v[98:99]
	s_waitcnt lgkmcnt(0)
	v_add_f32_e32 v193, v193, v192
	ds_bpermute_b32 v192, v200, v193
	v_cvt_pk_bf16_f32 v108, v108, v109
	v_cvt_pk_bf16_f32 v109, v110, v111
	v_cvt_pk_bf16_f32 v110, v104, v105
	v_cvt_pk_bf16_f32 v111, v106, v107
	v_cvt_pk_bf16_f32 v100, v100, v101
	v_cvt_pk_bf16_f32 v101, v102, v103
	v_cvt_pk_bf16_f32 v102, v96, v97
	v_cvt_pk_bf16_f32 v103, v98, v99
	s_waitcnt lgkmcnt(0)
	v_add_f32_e32 v193, v193, v192
	global_store_dwordx4 v190, v[108:111], s[26:27]
	global_store_dwordx4 v190, v[100:103], s[26:27] offset:256
	s_add_u32 s26, s26, 0x8000
	s_addc_u32 s27, s27, 0
	s_and_saveexec_b64 s[100:101], vcc
	s_cbranch_execz .Lepit_op_na2
	global_atomic_add_f32 v191, v193, s[54:55] offset:128
.Lepit_op_na2:
	s_or_b64 exec, exec, s[100:101]
	s_waitcnt lgkmcnt(0)
	global_load_dwordx4 v[60:63], v189, s[22:23]
	global_load_dwordx4 v[56:59], v189, s[22:23] offset:16
	global_load_dwordx4 v[52:55], v189, s[22:23] offset:512
	global_load_dwordx4 v[48:51], v189, s[22:23] offset:528
	s_add_u32 s22, s22, 0x10000
	s_addc_u32 s23, s23, 0
	s_waitcnt vmcnt(10)
	v_pk_fma_f32 v[92:93], v[154:155], v[72:73], v[92:93]
	v_pk_fma_f32 v[94:95], v[156:157], v[74:75], v[94:95]
	v_pk_fma_f32 v[88:89], v[158:159], v[80:81], v[88:89]
	v_pk_fma_f32 v[90:91], v[160:161], v[82:83], v[90:91]
	v_pk_fma_f32 v[84:85], v[162:163], v[64:65], v[84:85]
	v_pk_fma_f32 v[86:87], v[164:165], v[66:67], v[86:87]
	v_pk_fma_f32 v[76:77], v[224:225], v[68:69], v[76:77]
	v_pk_fma_f32 v[78:79], v[226:227], v[70:71], v[78:79]
	ds_bpermute_b32 v154, v195, v44
	ds_bpermute_b32 v155, v195, v45
	ds_bpermute_b32 v156, v195, v46
	ds_bpermute_b32 v157, v195, v47
	ds_bpermute_b32 v158, v195, v40
	ds_bpermute_b32 v159, v195, v41
	ds_bpermute_b32 v160, v195, v42
	ds_bpermute_b32 v161, v195, v43
	global_store_dwordx4 v189, v[92:95], s[24:25]
	global_store_dwordx4 v189, v[88:91], s[24:25] offset:16
	global_store_dwordx4 v189, v[84:87], s[24:25] offset:512
	global_store_dwordx4 v189, v[76:79], s[24:25] offset:528
	s_add_u32 s24, s24, 0x50000
	s_addc_u32 s25, s25, 0
	s_waitcnt lgkmcnt(6)
	ds_bpermute_b32 v162, v195, v36
	ds_bpermute_b32 v163, v195, v37
	ds_bpermute_b32 v164, v195, v38
	ds_bpermute_b32 v165, v195, v39
	ds_bpermute_b32 v224, v195, v32
	ds_bpermute_b32 v225, v195, v33
	ds_bpermute_b32 v226, v195, v34
	ds_bpermute_b32 v227, v195, v35
	v_pk_mul_f32 v[168:169], v[92:93], v[92:93]
	v_pk_fma_f32 v[168:169], v[94:95], v[94:95], v[168:169]
	v_pk_fma_f32 v[168:169], v[88:89], v[88:89], v[168:169]
	v_pk_fma_f32 v[168:169], v[90:91], v[90:91], v[168:169]
	v_pk_fma_f32 v[168:169], v[84:85], v[84:85], v[168:169]
	v_pk_fma_f32 v[168:169], v[86:87], v[86:87], v[168:169]
	v_pk_fma_f32 v[168:169], v[76:77], v[76:77], v[168:169]
	v_pk_fma_f32 v[168:169], v[78:79], v[78:79], v[168:169]
	v_add_f32_e32 v193, v168, v169
	ds_bpermute_b32 v192, v188, v193
	v_pk_mul_f32 v[92:93], v[174:175], v[92:93]
	v_pk_mul_f32 v[94:95], v[176:177], v[94:95]
	v_pk_mul_f32 v[88:89], v[184:185], v[88:89]
	v_pk_mul_f32 v[90:91], v[186:187], v[90:91]
	v_pk_mul_f32 v[84:85], v[170:171], v[84:85]
	v_pk_mul_f32 v[86:87], v[172:173], v[86:87]
	v_pk_mul_f32 v[76:77], v[178:179], v[76:77]
	v_pk_mul_f32 v[78:79], v[180:181], v[78:79]
	s_waitcnt lgkmcnt(0)
	v_add_f32_e32 v193, v193, v192
	ds_bpermute_b32 v192, v200, v193
	v_cvt_pk_bf16_f32 v92, v92, v93
	v_cvt_pk_bf16_f32 v93, v94, v95
	v_cvt_pk_bf16_f32 v94, v88, v89
	v_cvt_pk_bf16_f32 v95, v90, v91
	v_cvt_pk_bf16_f32 v84, v84, v85
	v_cvt_pk_bf16_f32 v85, v86, v87
	v_cvt_pk_bf16_f32 v86, v76, v77
	v_cvt_pk_bf16_f32 v87, v78, v79
	s_waitcnt lgkmcnt(0)
	v_add_f32_e32 v193, v193, v192
	global_store_dwordx4 v190, v[92:95], s[26:27]
	global_store_dwordx4 v190, v[84:87], s[26:27] offset:256
	s_add_u32 s26, s26, 0x28000
	s_addc_u32 s27, s27, 0
	s_and_saveexec_b64 s[100:101], vcc
	s_cbranch_execz .Lepit_op_na3
	global_atomic_add_f32 v191, v193, s[54:55] offset:192
.Lepit_op_na3:
	s_or_b64 exec, exec, s[100:101]
	s_waitcnt lgkmcnt(0)
	global_load_dwordx4 v[44:47], v189, s[22:23]
	global_load_dwordx4 v[40:43], v189, s[22:23] offset:16
	global_load_dwordx4 v[36:39], v189, s[22:23] offset:512
	global_load_dwordx4 v[32:35], v189, s[22:23] offset:528
	s_add_u32 s22, s22, 0x10000
	s_addc_u32 s23, s23, 0
	s_waitcnt vmcnt(10)
	v_pk_fma_f32 v[60:61], v[208:209], v[72:73], v[60:61]
	v_pk_fma_f32 v[62:63], v[210:211], v[74:75], v[62:63]
	v_pk_fma_f32 v[56:57], v[212:213], v[80:81], v[56:57]
	v_pk_fma_f32 v[58:59], v[214:215], v[82:83], v[58:59]
	v_pk_fma_f32 v[52:53], v[216:217], v[64:65], v[52:53]
	v_pk_fma_f32 v[54:55], v[218:219], v[66:67], v[54:55]
	v_pk_fma_f32 v[48:49], v[220:221], v[68:69], v[48:49]
	v_pk_fma_f32 v[50:51], v[222:223], v[70:71], v[50:51]
	ds_bpermute_b32 v208, v195, v28
	ds_bpermute_b32 v209, v195, v29
	ds_bpermute_b32 v210, v195, v30
	ds_bpermute_b32 v211, v195, v31
	ds_bpermute_b32 v212, v195, v24
	ds_bpermute_b32 v213, v195, v25
	ds_bpermute_b32 v214, v195, v26
	ds_bpermute_b32 v215, v195, v27
	global_store_dwordx4 v189, v[60:63], s[24:25]
	global_store_dwordx4 v189, v[56:59], s[24:25] offset:16
	global_store_dwordx4 v189, v[52:55], s[24:25] offset:512
	global_store_dwordx4 v189, v[48:51], s[24:25] offset:528
	s_add_u32 s24, s24, 0x10000
	s_addc_u32 s25, s25, 0
	s_waitcnt lgkmcnt(6)
	ds_bpermute_b32 v216, v195, v20
	ds_bpermute_b32 v217, v195, v21
	ds_bpermute_b32 v218, v195, v22
	ds_bpermute_b32 v219, v195, v23
	ds_bpermute_b32 v220, v195, v16
	ds_bpermute_b32 v221, v195, v17
	ds_bpermute_b32 v222, v195, v18
	ds_bpermute_b32 v223, v195, v19
	v_pk_mul_f32 v[168:169], v[60:61], v[60:61]
	v_pk_fma_f32 v[168:169], v[62:63], v[62:63], v[168:169]
	v_pk_fma_f32 v[168:169], v[56:57], v[56:57], v[168:169]
	v_pk_fma_f32 v[168:169], v[58:59], v[58:59], v[168:169]
	v_pk_fma_f32 v[168:169], v[52:53], v[52:53], v[168:169]
	v_pk_fma_f32 v[168:169], v[54:55], v[54:55], v[168:169]
	v_pk_fma_f32 v[168:169], v[48:49], v[48:49], v[168:169]
	v_pk_fma_f32 v[168:169], v[50:51], v[50:51], v[168:169]
	v_add_f32_e32 v193, v168, v169
	ds_bpermute_b32 v192, v188, v193
	v_pk_mul_f32 v[60:61], v[174:175], v[60:61]
	v_pk_mul_f32 v[62:63], v[176:177], v[62:63]
	v_pk_mul_f32 v[56:57], v[184:185], v[56:57]
	v_pk_mul_f32 v[58:59], v[186:187], v[58:59]
	v_pk_mul_f32 v[52:53], v[170:171], v[52:53]
	v_pk_mul_f32 v[54:55], v[172:173], v[54:55]
	v_pk_mul_f32 v[48:49], v[178:179], v[48:49]
	v_pk_mul_f32 v[50:51], v[180:181], v[50:51]
	s_waitcnt lgkmcnt(0)
	v_add_f32_e32 v193, v193, v192
	ds_bpermute_b32 v192, v200, v193
	v_cvt_pk_bf16_f32 v60, v60, v61
	v_cvt_pk_bf16_f32 v61, v62, v63
	v_cvt_pk_bf16_f32 v62, v56, v57
	v_cvt_pk_bf16_f32 v63, v58, v59
	v_cvt_pk_bf16_f32 v52, v52, v53
	v_cvt_pk_bf16_f32 v53, v54, v55
	v_cvt_pk_bf16_f32 v54, v48, v49
	v_cvt_pk_bf16_f32 v55, v50, v51
	s_waitcnt lgkmcnt(0)
	v_add_f32_e32 v193, v193, v192
	global_store_dwordx4 v190, v[60:63], s[26:27]
	global_store_dwordx4 v190, v[52:55], s[26:27] offset:256
	s_add_u32 s26, s26, 0x8000
	s_addc_u32 s27, s27, 0
	s_and_saveexec_b64 s[100:101], vcc
	s_cbranch_execz .Lepit_op_na4
	global_atomic_add_f32 v191, v193, s[54:55] offset:512
.Lepit_op_na4:
	s_or_b64 exec, exec, s[100:101]
	s_waitcnt lgkmcnt(0)
	global_load_dwordx4 v[28:31], v189, s[22:23]
	global_load_dwordx4 v[24:27], v189, s[22:23] offset:16
	global_load_dwordx4 v[20:23], v189, s[22:23] offset:512
	global_load_dwordx4 v[16:19], v189, s[22:23] offset:528
	s_add_u32 s22, s22, 0x10000
	s_addc_u32 s23, s23, 0
	s_waitcnt vmcnt(10)
	v_pk_fma_f32 v[44:45], v[154:155], v[72:73], v[44:45]
	v_pk_fma_f32 v[46:47], v[156:157], v[74:75], v[46:47]
	v_pk_fma_f32 v[40:41], v[158:159], v[80:81], v[40:41]
	v_pk_fma_f32 v[42:43], v[160:161], v[82:83], v[42:43]
	v_pk_fma_f32 v[36:37], v[162:163], v[64:65], v[36:37]
	v_pk_fma_f32 v[38:39], v[164:165], v[66:67], v[38:39]
	v_pk_fma_f32 v[32:33], v[224:225], v[68:69], v[32:33]
	v_pk_fma_f32 v[34:35], v[226:227], v[70:71], v[34:35]
	ds_bpermute_b32 v154, v195, v12
	ds_bpermute_b32 v155, v195, v13
	ds_bpermute_b32 v156, v195, v14
	ds_bpermute_b32 v157, v195, v15
	ds_bpermute_b32 v158, v195, v8
	ds_bpermute_b32 v159, v195, v9
	ds_bpermute_b32 v160, v195, v10
	ds_bpermute_b32 v161, v195, v11
	global_store_dwordx4 v189, v[44:47], s[24:25]
	global_store_dwordx4 v189, v[40:43], s[24:25] offset:16
	global_store_dwordx4 v189, v[36:39], s[24:25] offset:512
	global_store_dwordx4 v189, v[32:35], s[24:25] offset:528
	s_add_u32 s24, s24, 0x10000
	s_addc_u32 s25, s25, 0
	s_waitcnt lgkmcnt(6)
	ds_bpermute_b32 v162, v195, v4
	ds_bpermute_b32 v163, v195, v5
	ds_bpermute_b32 v164, v195, v6
	ds_bpermute_b32 v165, v195, v7
	ds_bpermute_b32 v224, v195, v0
	ds_bpermute_b32 v225, v195, v1
	ds_bpermute_b32 v226, v195, v2
	ds_bpermute_b32 v227, v195, v3
	v_pk_mul_f32 v[168:169], v[44:45], v[44:45]
	v_pk_fma_f32 v[168:169], v[46:47], v[46:47], v[168:169]
	v_pk_fma_f32 v[168:169], v[40:41], v[40:41], v[168:169]
	v_pk_fma_f32 v[168:169], v[42:43], v[42:43], v[168:169]
	v_pk_fma_f32 v[168:169], v[36:37], v[36:37], v[168:169]
	v_pk_fma_f32 v[168:169], v[38:39], v[38:39], v[168:169]
	v_pk_fma_f32 v[168:169], v[32:33], v[32:33], v[168:169]
	v_pk_fma_f32 v[168:169], v[34:35], v[34:35], v[168:169]
	v_add_f32_e32 v193, v168, v169
	ds_bpermute_b32 v192, v188, v193
	v_pk_mul_f32 v[44:45], v[174:175], v[44:45]
	v_pk_mul_f32 v[46:47], v[176:177], v[46:47]
	v_pk_mul_f32 v[40:41], v[184:185], v[40:41]
	v_pk_mul_f32 v[42:43], v[186:187], v[42:43]
	v_pk_mul_f32 v[36:37], v[170:171], v[36:37]
	v_pk_mul_f32 v[38:39], v[172:173], v[38:39]
	v_pk_mul_f32 v[32:33], v[178:179], v[32:33]
	v_pk_mul_f32 v[34:35], v[180:181], v[34:35]
	s_waitcnt lgkmcnt(0)
	v_add_f32_e32 v193, v193, v192
	ds_bpermute_b32 v192, v200, v193
	v_cvt_pk_bf16_f32 v44, v44, v45
	v_cvt_pk_bf16_f32 v45, v46, v47
	v_cvt_pk_bf16_f32 v46, v40, v41
	v_cvt_pk_bf16_f32 v47, v42, v43
	v_cvt_pk_bf16_f32 v36, v36, v37
	v_cvt_pk_bf16_f32 v37, v38, v39
	v_cvt_pk_bf16_f32 v38, v32, v33
	v_cvt_pk_bf16_f32 v39, v34, v35
	s_waitcnt lgkmcnt(0)
	v_add_f32_e32 v193, v193, v192
	global_store_dwordx4 v190, v[44:47], s[26:27]
	global_store_dwordx4 v190, v[36:39], s[26:27] offset:256
	s_add_u32 s26, s26, 0x8000
	s_addc_u32 s27, s27, 0
	s_and_saveexec_b64 s[100:101], vcc
	s_cbranch_execz .Lepit_op_na5
	global_atomic_add_f32 v191, v193, s[54:55] offset:576
.Lepit_op_na5:
	s_or_b64 exec, exec, s[100:101]
	s_waitcnt lgkmcnt(0)
	global_load_dwordx4 v[12:15], v189, s[22:23]
	global_load_dwordx4 v[8:11], v189, s[22:23] offset:16
	global_load_dwordx4 v[4:7], v189, s[22:23] offset:512
	global_load_dwordx4 v[0:3], v189, s[22:23] offset:528
	s_waitcnt vmcnt(10)
	v_pk_fma_f32 v[28:29], v[208:209], v[72:73], v[28:29]
	v_pk_fma_f32 v[30:31], v[210:211], v[74:75], v[30:31]
	v_pk_fma_f32 v[24:25], v[212:213], v[80:81], v[24:25]
	v_pk_fma_f32 v[26:27], v[214:215], v[82:83], v[26:27]
	v_pk_fma_f32 v[20:21], v[216:217], v[64:65], v[20:21]
	v_pk_fma_f32 v[22:23], v[218:219], v[66:67], v[22:23]
	v_pk_fma_f32 v[16:17], v[220:221], v[68:69], v[16:17]
	v_pk_fma_f32 v[18:19], v[222:223], v[70:71], v[18:19]
	global_store_dwordx4 v189, v[28:31], s[24:25]
	global_store_dwordx4 v189, v[24:27], s[24:25] offset:16
	global_store_dwordx4 v189, v[20:23], s[24:25] offset:512
	global_store_dwordx4 v189, v[16:19], s[24:25] offset:528
	s_add_u32 s24, s24, 0x10000
	s_addc_u32 s25, s25, 0
	v_pk_mul_f32 v[168:169], v[28:29], v[28:29]
	v_pk_fma_f32 v[168:169], v[30:31], v[30:31], v[168:169]
	v_pk_fma_f32 v[168:169], v[24:25], v[24:25], v[168:169]
	v_pk_fma_f32 v[168:169], v[26:27], v[26:27], v[168:169]
	v_pk_fma_f32 v[168:169], v[20:21], v[20:21], v[168:169]
	v_pk_fma_f32 v[168:169], v[22:23], v[22:23], v[168:169]
	v_pk_fma_f32 v[168:169], v[16:17], v[16:17], v[168:169]
	v_pk_fma_f32 v[168:169], v[18:19], v[18:19], v[168:169]
	v_add_f32_e32 v193, v168, v169
	ds_bpermute_b32 v192, v188, v193
	v_pk_mul_f32 v[28:29], v[174:175], v[28:29]
	v_pk_mul_f32 v[30:31], v[176:177], v[30:31]
	v_pk_mul_f32 v[24:25], v[184:185], v[24:25]
	v_pk_mul_f32 v[26:27], v[186:187], v[26:27]
	v_pk_mul_f32 v[20:21], v[170:171], v[20:21]
	v_pk_mul_f32 v[22:23], v[172:173], v[22:23]
	v_pk_mul_f32 v[16:17], v[178:179], v[16:17]
	v_pk_mul_f32 v[18:19], v[180:181], v[18:19]
	s_waitcnt lgkmcnt(0)
	v_add_f32_e32 v193, v193, v192
	ds_bpermute_b32 v192, v200, v193
	v_cvt_pk_bf16_f32 v28, v28, v29
	v_cvt_pk_bf16_f32 v29, v30, v31
	v_cvt_pk_bf16_f32 v30, v24, v25
	v_cvt_pk_bf16_f32 v31, v26, v27
	v_cvt_pk_bf16_f32 v20, v20, v21
	v_cvt_pk_bf16_f32 v21, v22, v23
	v_cvt_pk_bf16_f32 v22, v16, v17
	v_cvt_pk_bf16_f32 v23, v18, v19
	s_waitcnt lgkmcnt(0)
	v_add_f32_e32 v193, v193, v192
	global_store_dwordx4 v190, v[28:31], s[26:27]
	global_store_dwordx4 v190, v[20:23], s[26:27] offset:256
	s_add_u32 s26, s26, 0x8000
	s_addc_u32 s27, s27, 0
	s_and_saveexec_b64 s[100:101], vcc
	s_cbranch_execz .Lepit_op_na6
	global_atomic_add_f32 v191, v193, s[54:55] offset:640
.Lepit_op_na6:
	s_or_b64 exec, exec, s[100:101]
	s_waitcnt vmcnt(6)
	v_pk_fma_f32 v[12:13], v[154:155], v[72:73], v[12:13]
	v_pk_fma_f32 v[14:15], v[156:157], v[74:75], v[14:15]
	v_pk_fma_f32 v[8:9], v[158:159], v[80:81], v[8:9]
	v_pk_fma_f32 v[10:11], v[160:161], v[82:83], v[10:11]
	v_pk_fma_f32 v[4:5], v[162:163], v[64:65], v[4:5]
	v_pk_fma_f32 v[6:7], v[164:165], v[66:67], v[6:7]
	v_pk_fma_f32 v[0:1], v[224:225], v[68:69], v[0:1]
	v_pk_fma_f32 v[2:3], v[226:227], v[70:71], v[2:3]
	global_store_dwordx4 v189, v[12:15], s[24:25]
	global_store_dwordx4 v189, v[8:11], s[24:25] offset:16
	global_store_dwordx4 v189, v[4:7], s[24:25] offset:512
	global_store_dwordx4 v189, v[0:3], s[24:25] offset:528
	v_pk_mul_f32 v[168:169], v[12:13], v[12:13]
	v_pk_fma_f32 v[168:169], v[14:15], v[14:15], v[168:169]
	v_pk_fma_f32 v[168:169], v[8:9], v[8:9], v[168:169]
	v_pk_fma_f32 v[168:169], v[10:11], v[10:11], v[168:169]
	v_pk_fma_f32 v[168:169], v[4:5], v[4:5], v[168:169]
	v_pk_fma_f32 v[168:169], v[6:7], v[6:7], v[168:169]
	v_pk_fma_f32 v[168:169], v[0:1], v[0:1], v[168:169]
	v_pk_fma_f32 v[168:169], v[2:3], v[2:3], v[168:169]
	v_add_f32_e32 v193, v168, v169
	ds_bpermute_b32 v192, v188, v193
	v_pk_mul_f32 v[12:13], v[174:175], v[12:13]
	v_pk_mul_f32 v[14:15], v[176:177], v[14:15]
	v_pk_mul_f32 v[8:9], v[184:185], v[8:9]
	v_pk_mul_f32 v[10:11], v[186:187], v[10:11]
	v_pk_mul_f32 v[4:5], v[170:171], v[4:5]
	v_pk_mul_f32 v[6:7], v[172:173], v[6:7]
	v_pk_mul_f32 v[0:1], v[178:179], v[0:1]
	v_pk_mul_f32 v[2:3], v[180:181], v[2:3]
	s_waitcnt lgkmcnt(0)
	v_add_f32_e32 v193, v193, v192
	ds_bpermute_b32 v192, v200, v193
	v_cvt_pk_bf16_f32 v12, v12, v13
	v_cvt_pk_bf16_f32 v13, v14, v15
	v_cvt_pk_bf16_f32 v14, v8, v9
	v_cvt_pk_bf16_f32 v15, v10, v11
	v_cvt_pk_bf16_f32 v4, v4, v5
	v_cvt_pk_bf16_f32 v5, v6, v7
	v_cvt_pk_bf16_f32 v6, v0, v1
	v_cvt_pk_bf16_f32 v7, v2, v3
	s_waitcnt lgkmcnt(0)
	v_add_f32_e32 v193, v193, v192
	global_store_dwordx4 v190, v[12:15], s[26:27]
	global_store_dwordx4 v190, v[4:7], s[26:27] offset:256
	s_and_saveexec_b64 s[100:101], vcc
	s_cbranch_execz .Lepit_op_na7
	global_atomic_add_f32 v191, v193, s[54:55] offset:704
